# nt policy on both attention outputs (dense YA and dilated YB stores), on top of nt7
# baseline (speedup 1.0000x reference)
; __device__ __forceinline__ int crow(int r, int hi) { return (r & 3) + 8 * (r >> 2) + 4 * hi; }
;     ...
;   if (hi == 0) li_l[r32] = l_reg; asm volatile("s_waitcnt lgkmcnt(0)" ::: "memory");
;   if constexpr (DIL) { if (hi == 0) lse_o[(long)(wid * QBLK + r32) * lse_s] = m_reg + __log2f(l_reg); }
;   float rli[16];
; #pragma unroll
;   for (int r = 0; r < 16; ++r) rli[r] = __builtin_amdgcn_rcpf(li_l[crow(r, hi)]);
;   bf16* Ow = Ob + (long)(wid * QBLK) * os;
;     ...
;   { char* stg = DIL ? ((wid < 4 ? K_lds : V_lds) + 2 * SHM_K + (wid & 3) * 8192) : (K_lds + wid * 8192);
; #pragma unroll
;     for (int r = 0; r < 16; ++r) { const int orow = crow(r, hi);
; #pragma unroll
;       for (int d0 = 0; d0 < 4; ++d0) *(bf16*)(stg + orow * 256 + (d0 * 32 + r32) * 2) = __float2bfloat16(o[d0][r] * rli[r]); }
.LBB0_48:
	s_or_b64 exec, exec, s[0:1]
	s_waitcnt lgkmcnt(0)
	v_add_u32_e32 v0, s12, v0
	ds_read_b128 v[66:69], v0
	ds_read_b128 v[70:73], v0 offset:32
	s_lshl_b64 s[0:1], s[2:3], 24
	s_add_u32 s0, s52, s0
	s_addc_u32 s1, s8, s1
	s_lshl_b32 s2, s51, 11
	s_waitcnt lgkmcnt(0)
	v_rcp_f32_e32 v74, v66
	v_rcp_f32_e32 v75, v67
	v_rcp_f32_e32 v76, v68
	v_rcp_f32_e32 v77, v69
	v_rcp_f32_e32 v78, v70
	ds_read_b128 v[66:69], v0 offset:64
	v_rcp_f32_e32 v79, v71
	v_rcp_f32_e32 v80, v72
	v_rcp_f32_e32 v81, v73
	ds_read_b128 v[70:73], v0 offset:96
	s_add_u32 s0, s0, s2
	s_addc_u32 s1, s1, 0
	s_lshl_b32 s2, s11, 8
	s_add_u32 s2, s0, s2
	s_addc_u32 s3, s1, 0
	s_ashr_i32 s51, s50, 31
	s_lshl_b32 s10, s10, 13
	s_waitcnt lgkmcnt(0)
	v_rcp_f32_e32 v0, v66
	v_rcp_f32_e32 v66, v67
	v_rcp_f32_e32 v67, v68
	v_rcp_f32_e32 v68, v69
	v_rcp_f32_e32 v69, v70
	v_rcp_f32_e32 v70, v71
	v_rcp_f32_e32 v71, v72
	v_rcp_f32_e32 v72, v73
	s_lshl_b64 s[0:1], s[50:51], 11
	s_add_i32 s10, s10, 0
	v_lshlrev_b32_e32 v73, 10, v233
	v_lshlrev_b32_e32 v82, 1, v232
	v_mul_f32_e32 v2, v2, v74
	v_add3_u32 v73, s10, v73, v82
	v_cvt_pk_bf16_f32 v2, v2, s0
	ds_write_b16 v73, v2
	v_mul_f32_e32 v2, v50, v74
	v_cvt_pk_bf16_f32 v2, v2, s0
	ds_write_b16 v73, v2 offset:64
	v_mul_f32_e32 v2, v34, v74
	v_cvt_pk_bf16_f32 v2, v2, s0
	ds_write_b16 v73, v2 offset:128
	v_mul_f32_e32 v2, v18, v74
	v_cvt_pk_bf16_f32 v2, v2, s0
	ds_write_b16 v73, v2 offset:192
	v_mul_f32_e32 v2, v3, v75
	v_cvt_pk_bf16_f32 v2, v2, s0
	ds_write_b16 v73, v2 offset:256
	v_mul_f32_e32 v2, v51, v75
	v_cvt_pk_bf16_f32 v2, v2, s0
	ds_write_b16 v73, v2 offset:320
	v_mul_f32_e32 v2, v35, v75
	v_cvt_pk_bf16_f32 v2, v2, s0
	ds_write_b16 v73, v2 offset:384
	v_mul_f32_e32 v2, v19, v75
	v_cvt_pk_bf16_f32 v2, v2, s0
	ds_write_b16 v73, v2 offset:448
	v_mul_f32_e32 v2, v4, v76
	v_cvt_pk_bf16_f32 v2, v2, s0
	ds_write_b16 v73, v2 offset:512
	v_mul_f32_e32 v2, v52, v76
	v_cvt_pk_bf16_f32 v2, v2, s0
	ds_write_b16 v73, v2 offset:576
	v_mul_f32_e32 v2, v36, v76
	v_cvt_pk_bf16_f32 v2, v2, s0
	ds_write_b16 v73, v2 offset:640
	v_mul_f32_e32 v2, v20, v76
	v_cvt_pk_bf16_f32 v2, v2, s0
	ds_write_b16 v73, v2 offset:704
	v_mul_f32_e32 v2, v5, v77
	v_cvt_pk_bf16_f32 v2, v2, s0
	ds_write_b16 v73, v2 offset:768
	v_mul_f32_e32 v2, v53, v77
	v_cvt_pk_bf16_f32 v2, v2, s0
	ds_write_b16 v73, v2 offset:832
	v_mul_f32_e32 v2, v37, v77
	v_cvt_pk_bf16_f32 v2, v2, s0
	ds_write_b16 v73, v2 offset:896
	v_mul_f32_e32 v2, v21, v77
	v_cvt_pk_bf16_f32 v2, v2, s0
	ds_write_b16 v73, v2 offset:960
	v_mul_f32_e32 v2, v6, v78
	v_cvt_pk_bf16_f32 v2, v2, s0
	ds_write_b16 v73, v2 offset:2048
	v_mul_f32_e32 v2, v54, v78
	v_cvt_pk_bf16_f32 v2, v2, s0
	ds_write_b16 v73, v2 offset:2112
	v_mul_f32_e32 v2, v38, v78
	v_cvt_pk_bf16_f32 v2, v2, s0
	ds_write_b16 v73, v2 offset:2176
	v_mul_f32_e32 v2, v22, v78
	v_cvt_pk_bf16_f32 v2, v2, s0
	ds_write_b16 v73, v2 offset:2240
	v_mul_f32_e32 v2, v7, v79
	v_cvt_pk_bf16_f32 v2, v2, s0
	ds_write_b16 v73, v2 offset:2304
	v_mul_f32_e32 v2, v55, v79
	v_cvt_pk_bf16_f32 v2, v2, s0
	ds_write_b16 v73, v2 offset:2368
	v_mul_f32_e32 v2, v39, v79
	v_cvt_pk_bf16_f32 v2, v2, s0
	ds_write_b16 v73, v2 offset:2432
	v_mul_f32_e32 v2, v23, v79
	v_cvt_pk_bf16_f32 v2, v2, s0
	ds_write_b16 v73, v2 offset:2496
	v_mul_f32_e32 v2, v8, v80
	v_cvt_pk_bf16_f32 v2, v2, s0
	ds_write_b16 v73, v2 offset:2560
	v_mul_f32_e32 v2, v56, v80
	v_cvt_pk_bf16_f32 v2, v2, s0
	ds_write_b16 v73, v2 offset:2624
	v_mul_f32_e32 v2, v40, v80
	v_cvt_pk_bf16_f32 v2, v2, s0
	ds_write_b16 v73, v2 offset:2688
	v_mul_f32_e32 v2, v24, v80
	v_cvt_pk_bf16_f32 v2, v2, s0
	ds_write_b16 v73, v2 offset:2752
	v_mul_f32_e32 v2, v9, v81
	v_cvt_pk_bf16_f32 v2, v2, s0
	ds_write_b16 v73, v2 offset:2816
	v_mul_f32_e32 v2, v57, v81
	v_cvt_pk_bf16_f32 v2, v2, s0
	ds_write_b16 v73, v2 offset:2880
	v_mul_f32_e32 v2, v41, v81
	v_cvt_pk_bf16_f32 v2, v2, s0
	ds_write_b16 v73, v2 offset:2944
	v_mul_f32_e32 v2, v25, v81
	v_cvt_pk_bf16_f32 v2, v2, s0
	ds_write_b16 v73, v2 offset:3008
	v_mul_f32_e32 v2, v10, v0
	v_cvt_pk_bf16_f32 v2, v2, s0
	ds_write_b16 v73, v2 offset:4096
	v_mul_f32_e32 v2, v58, v0
	v_cvt_pk_bf16_f32 v2, v2, s0
	ds_write_b16 v73, v2 offset:4160
	v_mul_f32_e32 v2, v42, v0
	v_mul_f32_e32 v0, v26, v0
	v_cvt_pk_bf16_f32 v0, v0, s0
	ds_write_b16 v73, v0 offset:4288
	v_mul_f32_e32 v0, v11, v66
	v_cvt_pk_bf16_f32 v0, v0, s0
	ds_write_b16 v73, v0 offset:4352
	v_mul_f32_e32 v0, v59, v66
	v_cvt_pk_bf16_f32 v0, v0, s0
	ds_write_b16 v73, v0 offset:4416
	v_mul_f32_e32 v0, v43, v66
	v_cvt_pk_bf16_f32 v0, v0, s0
	ds_write_b16 v73, v0 offset:4480
	v_mul_f32_e32 v0, v27, v66
	v_cvt_pk_bf16_f32 v0, v0, s0
	ds_write_b16 v73, v0 offset:4544
	v_mul_f32_e32 v0, v12, v67
	v_cvt_pk_bf16_f32 v0, v0, s0
	ds_write_b16 v73, v0 offset:4608
	v_mul_f32_e32 v0, v60, v67
	v_cvt_pk_bf16_f32 v0, v0, s0
	ds_write_b16 v73, v0 offset:4672
	v_mul_f32_e32 v0, v44, v67
	v_cvt_pk_bf16_f32 v0, v0, s0
	ds_write_b16 v73, v0 offset:4736
	v_mul_f32_e32 v0, v28, v67
	v_cvt_pk_bf16_f32 v0, v0, s0
	ds_write_b16 v73, v0 offset:4800
	v_mul_f32_e32 v0, v13, v68
	v_cvt_pk_bf16_f32 v0, v0, s0
	ds_write_b16 v73, v0 offset:4864
	v_mul_f32_e32 v0, v61, v68
	v_cvt_pk_bf16_f32 v0, v0, s0
	ds_write_b16 v73, v0 offset:4928
	v_mul_f32_e32 v0, v45, v68
	v_cvt_pk_bf16_f32 v0, v0, s0
	ds_write_b16 v73, v0 offset:4992
	v_mul_f32_e32 v0, v29, v68
	v_cvt_pk_bf16_f32 v0, v0, s0
	ds_write_b16 v73, v0 offset:5056
	v_mul_f32_e32 v0, v14, v69
	v_cvt_pk_bf16_f32 v0, v0, s0
	ds_write_b16 v73, v0 offset:6144
	v_mul_f32_e32 v0, v62, v69
	v_cvt_pk_bf16_f32 v0, v0, s0
	ds_write_b16 v73, v0 offset:6208
	v_mul_f32_e32 v0, v46, v69
	v_cvt_pk_bf16_f32 v0, v0, s0
	ds_write_b16 v73, v0 offset:6272
	v_mul_f32_e32 v0, v30, v69
	v_cvt_pk_bf16_f32 v0, v0, s0
	ds_write_b16 v73, v0 offset:6336
	v_mul_f32_e32 v0, v15, v70
	v_cvt_pk_bf16_f32 v0, v0, s0
	ds_write_b16 v73, v0 offset:6400
	v_mul_f32_e32 v0, v63, v70
	v_cvt_pk_bf16_f32 v0, v0, s0
	ds_write_b16 v73, v0 offset:6464
	v_mul_f32_e32 v0, v47, v70
	v_cvt_pk_bf16_f32 v0, v0, s0
	ds_write_b16 v73, v0 offset:6528
	v_mul_f32_e32 v0, v31, v70
	v_cvt_pk_bf16_f32 v0, v0, s0
	ds_write_b16 v73, v0 offset:6592
	v_mul_f32_e32 v0, v16, v71
	v_cvt_pk_bf16_f32 v0, v0, s0
	ds_write_b16 v73, v0 offset:6656
	v_mul_f32_e32 v0, v64, v71
	v_cvt_pk_bf16_f32 v0, v0, s0
	ds_write_b16 v73, v0 offset:6720
	v_mul_f32_e32 v0, v48, v71
	v_cvt_pk_bf16_f32 v0, v0, s0
	ds_write_b16 v73, v0 offset:6784
	v_mul_f32_e32 v0, v32, v71
	v_cvt_pk_bf16_f32 v0, v0, s0
	ds_write_b16 v73, v0 offset:6848
	v_mul_f32_e32 v0, v17, v72
	v_cvt_pk_bf16_f32 v0, v0, s0
	ds_write_b16 v73, v0 offset:6912
	v_mul_f32_e32 v0, v65, v72
	v_cvt_pk_bf16_f32 v0, v0, s0
	ds_write_b16 v73, v0 offset:6976
	v_mul_f32_e32 v0, v49, v72
	v_cvt_pk_bf16_f32 v0, v0, s0
	ds_write_b16 v73, v0 offset:7040
	v_mul_f32_e32 v0, v33, v72
	v_cvt_pk_bf16_f32 v0, v0, s0
	v_cvt_pk_bf16_f32 v2, v2, s0
	ds_write_b16 v73, v0 offset:7104
	s_add_u32 s0, s2, s0
	v_lshlrev_b32_e32 v0, 4, v231
	ds_write_b16 v73, v2 offset:4224
	s_addc_u32 s1, s3, s1
	v_add_u32_e32 v14, s10, v0
	s_waitcnt lgkmcnt(0)
; #define DUPREP(k) for (int rep_ = 0; rep_ < 1 + ((MK_DUP >> (k)) & 1); ++rep_)
; __device__ __forceinline__ int crow(int r, int hi) { return (r & 3) + 8 * (r >> 2) + 4 * hi; }
;     ...
;     asm volatile("s_waitcnt lgkmcnt(0)" ::: "memory");
; #pragma unroll
;     for (int i = 0; i < 8; ++i) { const int row = i * 4 + (lane >> 4), ch = lane & 15;
;       const u32x4 v = *(const u32x4*)(stg + row * 256 + ch * 16);
;       *(u32x4*)(Ow + (long)row * os + ch * 8) = v; } }
;     ...
; #pragma unroll
;   for (int r = 0; r < 16; ++r) { const int orow = crow(r, hi);
; #pragma unroll
;     for (int d0 = 0; d0 < 4; ++d0) Ow[(long)orow * os + d0 * 32 + r32] = __float2bfloat16(o[d0][r] * rli[r]); }
;     ...
;   asm volatile("s_waitcnt lgkmcnt(0)\n\ts_barrier" ::: "memory");
; __global__ void __launch_bounds__(512, 2) mk_fwd(Params p) {
;     ...
;                 DUPREP(4) for (int u = vcu; u < 512; u += G) {
	v_lshl_add_u64 v[10:11], s[0:1], 0, v[0:1]
	v_lshl_add_u32 v0, v230, 8, v14
	v_or_b32_e32 v15, 4, v230
	ds_read_b128 v[2:5], v0
	v_lshl_add_u32 v6, v15, 8, v14
	ds_read_b128 v[6:9], v6
	v_lshlrev_b32_e32 v0, 11, v230
	v_lshl_add_u64 v[12:13], v[10:11], 0, v[0:1]
	v_lshlrev_b32_e32 v0, 11, v15
	s_waitcnt lgkmcnt(0)
	global_store_dwordx4 v[12:13], v[2:5], off nt
	v_or_b32_e32 v15, 12, v230
	s_add_i32 s25, s25, s98
	v_lshl_add_u64 v[2:3], v[10:11], 0, v[0:1]
	v_or_b32_e32 v0, 8, v230
	global_store_dwordx4 v[2:3], v[6:9], off nt
	v_lshl_add_u32 v2, v0, 8, v14
	ds_read_b128 v[2:5], v2
	v_lshl_add_u32 v6, v15, 8, v14
	ds_read_b128 v[6:9], v6
	v_lshlrev_b32_e32 v0, 11, v0
	v_lshl_add_u64 v[12:13], v[10:11], 0, v[0:1]
	v_lshlrev_b32_e32 v0, 11, v15
	s_waitcnt lgkmcnt(0)
	global_store_dwordx4 v[12:13], v[2:5], off nt
	v_or_b32_e32 v15, 20, v230
	s_cmpk_gt_i32 s25, 0x1ff
	v_lshl_add_u64 v[2:3], v[10:11], 0, v[0:1]
	v_or_b32_e32 v0, 16, v230
	global_store_dwordx4 v[2:3], v[6:9], off nt
	v_lshl_add_u32 v2, v0, 8, v14
	ds_read_b128 v[2:5], v2
	v_lshl_add_u32 v6, v15, 8, v14
	ds_read_b128 v[6:9], v6
	v_lshlrev_b32_e32 v0, 11, v0
	v_lshl_add_u64 v[12:13], v[10:11], 0, v[0:1]
	v_lshlrev_b32_e32 v0, 11, v15
	s_waitcnt lgkmcnt(0)
	global_store_dwordx4 v[12:13], v[2:5], off nt
	v_or_b32_e32 v15, 28, v230
	s_nop 0
	v_lshl_add_u64 v[2:3], v[10:11], 0, v[0:1]
	v_or_b32_e32 v0, 24, v230
	global_store_dwordx4 v[2:3], v[6:9], off nt
	v_lshl_add_u32 v2, v0, 8, v14
	ds_read_b128 v[2:5], v2
	v_lshl_add_u32 v6, v15, 8, v14
	ds_read_b128 v[6:9], v6
	v_lshlrev_b32_e32 v0, 11, v0
	v_lshl_add_u64 v[12:13], v[10:11], 0, v[0:1]
	v_lshlrev_b32_e32 v0, 11, v15
	s_waitcnt lgkmcnt(0)
	global_store_dwordx4 v[12:13], v[2:5], off nt
	s_nop 1
	v_lshl_add_u64 v[2:3], v[10:11], 0, v[0:1]
	global_store_dwordx4 v[2:3], v[6:9], off nt
	s_waitcnt lgkmcnt(0)
	s_barrier
	s_cbranch_scc1 .LBB0_124
